# P0b weight transposes: LDS read-backs issued eight at a time with counted waits instead of sixteen serial round trips
# speedup vs baseline: 1.0050x; 1.0033x over previous
.LBB0_78:
	s_lshl_b32 s15, s12, 1
	s_lshl_b32 s20, s0, 1
	v_or_b32_e32 v4, s20, v34
	s_add_i32 s30, s15, 4
	s_add_i32 s31, s20, 4
	v_mov_b32_e32 v43, v5
	s_add_i32 s47, s20, 8
	v_lshlrev_b64 v[56:57], 12, v[4:5]
	v_or_b32_e32 v42, s30, v3
	v_or_b32_e32 v4, s31, v34
	v_mov_b32_e32 v41, v5
	v_or_b32_e32 v40, s15, v3
	s_add_i32 s49, s20, 12
	v_lshlrev_b64 v[42:43], 12, v[42:43]
	v_lshlrev_b64 v[58:59], 12, v[4:5]
	v_or_b32_e32 v4, s47, v34
	s_add_i32 s46, s15, 8
	s_add_i32 s48, s15, 12
	s_add_i32 s56, s20, 16
	v_lshlrev_b64 v[40:41], 12, v[40:41]
	v_lshl_add_u64 v[56:57], v[32:33], 0, v[56:57]
	v_lshl_add_u64 v[42:43], v[32:33], 0, v[42:43]
	v_lshlrev_b64 v[60:61], 12, v[4:5]
	v_or_b32_e32 v4, s49, v34
	v_mov_b32_e32 v45, v5
	v_mov_b32_e32 v47, v5
	s_add_i32 s58, s20, 20
	v_or_b32_e32 v44, s46, v3
	v_or_b32_e32 v46, s48, v3
	v_lshl_add_u64 v[40:41], v[32:33], 0, v[40:41]
	v_lshl_add_u64 v[58:59], v[32:33], 0, v[58:59]
	global_load_dword v72, v[56:57], off
	global_load_dword v73, v[40:41], off
	global_load_dword v74, v[58:59], off
	global_load_dword v75, v[42:43], off
	v_lshlrev_b64 v[42:43], 12, v[4:5]
	v_or_b32_e32 v4, s56, v34
	s_add_i32 s55, s15, 16
	s_add_i32 s57, s15, 20
	s_add_i32 s60, s20, 24
	v_lshlrev_b64 v[44:45], 12, v[44:45]
	v_lshlrev_b64 v[46:47], 12, v[46:47]
	v_lshl_add_u64 v[40:41], v[32:33], 0, v[60:61]
	v_lshl_add_u64 v[42:43], v[32:33], 0, v[42:43]
	v_lshlrev_b64 v[56:57], 12, v[4:5]
	v_or_b32_e32 v4, s58, v34
	v_mov_b32_e32 v49, v5
	v_mov_b32_e32 v51, v5
	s_add_i32 s59, s15, 24
	s_add_i32 s61, s15, 28
	s_add_i32 s62, s20, 28
	v_or_b32_e32 v48, s55, v3
	v_or_b32_e32 v50, s57, v3
	v_lshl_add_u64 v[44:45], v[32:33], 0, v[44:45]
	v_lshl_add_u64 v[46:47], v[32:33], 0, v[46:47]
	global_load_dword v76, v[40:41], off
	global_load_dword v77, v[44:45], off
	global_load_dword v78, v[42:43], off
	global_load_dword v79, v[46:47], off
	v_lshlrev_b64 v[42:43], 12, v[4:5]
	v_or_b32_e32 v4, s60, v34
	v_mov_b32_e32 v53, v5
	v_mov_b32_e32 v55, v5
	v_or_b32_e32 v52, s59, v3
	v_or_b32_e32 v54, s61, v3
	v_lshlrev_b64 v[48:49], 12, v[48:49]
	v_lshlrev_b64 v[50:51], 12, v[50:51]
	v_lshl_add_u64 v[40:41], v[32:33], 0, v[56:57]
	v_lshl_add_u64 v[42:43], v[32:33], 0, v[42:43]
	v_lshlrev_b64 v[44:45], 12, v[4:5]
	v_or_b32_e32 v4, s62, v34
	v_lshlrev_b64 v[52:53], 12, v[52:53]
	v_lshlrev_b64 v[54:55], 12, v[54:55]
	v_lshl_add_u64 v[48:49], v[32:33], 0, v[48:49]
	v_lshl_add_u64 v[50:51], v[32:33], 0, v[50:51]
	global_load_dword v80, v[40:41], off
	global_load_dword v81, v[48:49], off
	global_load_dword v82, v[42:43], off
	global_load_dword v83, v[50:51], off
	v_lshl_add_u64 v[40:41], v[32:33], 0, v[44:45]
	v_lshlrev_b64 v[42:43], 12, v[4:5]
	v_lshl_add_u64 v[52:53], v[32:33], 0, v[52:53]
	v_lshl_add_u64 v[54:55], v[32:33], 0, v[54:55]
	v_lshl_add_u64 v[42:43], v[32:33], 0, v[42:43]
	global_load_dword v4, v[40:41], off
	global_load_dword v84, v[52:53], off
	global_load_dword v85, v[42:43], off
	global_load_dword v86, v[54:55], off
	v_or_b32_e32 v42, s15, v1
	v_or_b32_e32 v40, s20, v2
	s_add_i32 s0, s0, 16
	s_add_i32 s12, s12, 16
	s_add_i32 s13, s13, -16
	v_mad_u64_u32 v[40:41], s[20:21], v40, s5, v[8:9]
	v_mad_u64_u32 v[42:43], s[20:21], v42, s5, v[8:9]
	v_or_b32_e32 v41, s30, v1
	v_or_b32_e32 v43, s31, v2
	v_or_b32_e32 v50, s46, v1
	v_or_b32_e32 v48, s47, v2
	v_or_b32_e32 v54, s48, v1
	v_or_b32_e32 v52, s49, v2
	v_or_b32_e32 v58, s55, v1
	v_or_b32_e32 v56, s56, v2
	v_or_b32_e32 v62, s57, v1
	v_or_b32_e32 v60, s58, v2
	v_or_b32_e32 v66, s59, v1
	v_or_b32_e32 v64, s60, v2
	v_or_b32_e32 v70, s61, v1
	v_or_b32_e32 v68, s62, v2
	s_cmp_lg_u32 s13, 0
	v_mad_u64_u32 v[44:45], s[20:21], v43, s5, v[8:9]
	v_mad_u64_u32 v[46:47], s[20:21], v41, s5, v[8:9]
	v_mad_u64_u32 v[48:49], s[20:21], v48, s5, v[8:9]
	v_mad_u64_u32 v[50:51], s[20:21], v50, s5, v[8:9]
	v_mad_u64_u32 v[52:53], s[20:21], v52, s5, v[8:9]
	v_mad_u64_u32 v[54:55], s[20:21], v54, s5, v[8:9]
	v_mad_u64_u32 v[56:57], s[20:21], v56, s5, v[8:9]
	v_mad_u64_u32 v[58:59], s[20:21], v58, s5, v[8:9]
	v_mad_u64_u32 v[60:61], s[20:21], v60, s5, v[8:9]
	v_mad_u64_u32 v[62:63], s[20:21], v62, s5, v[8:9]
	v_mad_u64_u32 v[64:65], s[20:21], v64, s5, v[8:9]
	v_mad_u64_u32 v[66:67], s[20:21], v66, s5, v[8:9]
	v_mad_u64_u32 v[68:69], s[20:21], v68, s5, v[8:9]
	v_mad_u64_u32 v[70:71], s[20:21], v70, s5, v[8:9]
	s_waitcnt vmcnt(15)
	ds_write_b32 v40, v72
	s_waitcnt vmcnt(14)
	ds_write_b32 v42, v73
	s_waitcnt vmcnt(13)
	ds_write_b32 v44, v74
	s_waitcnt vmcnt(12)
	ds_write_b32 v46, v75
	s_waitcnt vmcnt(11)
	ds_write_b32 v48, v76
	s_waitcnt vmcnt(10)
	ds_write_b32 v50, v77
	s_waitcnt vmcnt(9)
	ds_write_b32 v52, v78
	s_waitcnt vmcnt(8)
	ds_write_b32 v54, v79
	s_waitcnt vmcnt(7)
	ds_write_b32 v56, v80
	s_waitcnt vmcnt(6)
	ds_write_b32 v58, v81
	s_waitcnt vmcnt(5)
	ds_write_b32 v60, v82
	s_waitcnt vmcnt(4)
	ds_write_b32 v62, v83
	s_waitcnt vmcnt(3)
	ds_write_b32 v64, v4
	s_waitcnt vmcnt(2)
	ds_write_b32 v66, v84
	s_waitcnt vmcnt(1)
	ds_write_b32 v68, v85
	s_waitcnt vmcnt(0)
	ds_write_b32 v70, v86
	s_cbranch_scc1 .LBB0_78
	s_waitcnt lgkmcnt(0)
	ds_read2_b32 v[72:73], v36 offset1:33
	ds_read2_b32 v[74:75], v36 offset0:66 offset1:99
	ds_read2_b32 v[76:77], v36 offset0:132 offset1:165
	ds_read2_b32 v[78:79], v36 offset0:198 offset1:231
	ds_read2_b32 v[80:81], v36 offset0:8 offset1:41
	ds_read2_b32 v[82:83], v36 offset0:74 offset1:107
	ds_read2_b32 v[84:85], v36 offset0:140 offset1:173
	ds_read2_b32 v[32:33], v36 offset0:206 offset1:239
	s_waitcnt lgkmcnt(7)
	v_cvt_pk_bf16_f32 v40, v72, v73
	s_waitcnt lgkmcnt(6)
	v_cvt_pk_bf16_f32 v41, v74, v75
	s_lshl_b32 s0, s7, 1
	v_or_b32_e32 v3, s6, v35
	s_waitcnt lgkmcnt(5)
	v_cvt_pk_bf16_f32 v42, v76, v77
	v_lshl_add_u64 v[44:45], v[10:11], 0, s[0:1]
	v_lshlrev_b32_e32 v4, 13, v3
	s_waitcnt lgkmcnt(4)
	v_cvt_pk_bf16_f32 v43, v78, v79
	v_lshl_add_u64 v[46:47], v[44:45], 0, v[4:5]
	global_store_dwordx4 v[46:47], v[40:43], off
	v_or_b32_e32 v3, s6, v37
	v_lshlrev_b32_e32 v4, 13, v3
	s_waitcnt lgkmcnt(3)
	v_cvt_pk_bf16_f32 v40, v80, v81
	s_waitcnt lgkmcnt(2)
	v_cvt_pk_bf16_f32 v41, v82, v83
	s_waitcnt lgkmcnt(1)
	v_cvt_pk_bf16_f32 v42, v84, v85
	s_waitcnt lgkmcnt(0)
	v_cvt_pk_bf16_f32 v43, v32, v33
	ds_read2_b32 v[72:73], v36 offset0:16 offset1:49
	ds_read2_b32 v[74:75], v36 offset0:82 offset1:115
	ds_read2_b32 v[76:77], v36 offset0:148 offset1:181
	ds_read2_b32 v[78:79], v36 offset0:214 offset1:247
	ds_read2_b32 v[80:81], v36 offset0:24 offset1:57
	ds_read2_b32 v[82:83], v36 offset0:90 offset1:123
	ds_read2_b32 v[84:85], v36 offset0:156 offset1:189
	ds_read2_b32 v[32:33], v36 offset0:222 offset1:255
	v_lshl_add_u64 v[46:47], v[44:45], 0, v[4:5]
	global_store_dwordx4 v[46:47], v[40:43], off
	v_or_b32_e32 v3, s6, v38
	v_lshlrev_b32_e32 v4, 13, v3
	s_waitcnt lgkmcnt(7)
	v_cvt_pk_bf16_f32 v40, v72, v73
	s_waitcnt lgkmcnt(6)
	v_cvt_pk_bf16_f32 v41, v74, v75
	s_waitcnt lgkmcnt(5)
	v_cvt_pk_bf16_f32 v42, v76, v77
	s_waitcnt lgkmcnt(4)
	v_cvt_pk_bf16_f32 v43, v78, v79
	v_lshl_add_u64 v[46:47], v[44:45], 0, v[4:5]
	global_store_dwordx4 v[46:47], v[40:43], off
	v_or_b32_e32 v3, s6, v39
	v_lshlrev_b32_e32 v4, 13, v3
	s_waitcnt lgkmcnt(3)
	v_cvt_pk_bf16_f32 v40, v80, v81
	s_waitcnt lgkmcnt(2)
	v_cvt_pk_bf16_f32 v41, v82, v83
	s_waitcnt lgkmcnt(1)
	v_cvt_pk_bf16_f32 v42, v84, v85
	s_waitcnt lgkmcnt(0)
	v_cvt_pk_bf16_f32 v43, v32, v33
	v_lshl_add_u64 v[32:33], v[44:45], 0, v[4:5]
	global_store_dwordx4 v[32:33], v[40:43], off
	s_waitcnt lgkmcnt(0)
	s_mov_b64 s[12:13], 0

.LBB0_82:
	s_lshl_b32 s13, s7, 1
	s_lshl_b32 s15, s0, 1
	v_or_b32_e32 v4, s15, v34
	s_add_i32 s30, s13, 4
	s_add_i32 s31, s15, 4
	v_mov_b32_e32 v43, v5
	s_add_i32 s47, s15, 8
	v_lshlrev_b64 v[56:57], 14, v[4:5]
	v_or_b32_e32 v42, s30, v3
	v_or_b32_e32 v4, s31, v34
	v_mov_b32_e32 v41, v5
	v_or_b32_e32 v40, s13, v3
	s_add_i32 s49, s15, 12
	v_lshlrev_b64 v[42:43], 14, v[42:43]
	v_lshlrev_b64 v[58:59], 14, v[4:5]
	v_or_b32_e32 v4, s47, v34
	s_add_i32 s46, s13, 8
	s_add_i32 s48, s13, 12
	s_add_i32 s56, s15, 16
	v_lshlrev_b64 v[40:41], 14, v[40:41]
	v_lshl_add_u64 v[56:57], v[32:33], 0, v[56:57]
	v_lshl_add_u64 v[42:43], v[32:33], 0, v[42:43]
	v_lshlrev_b64 v[60:61], 14, v[4:5]
	v_or_b32_e32 v4, s49, v34
	v_mov_b32_e32 v45, v5
	v_mov_b32_e32 v47, v5
	s_add_i32 s58, s15, 20
	v_or_b32_e32 v44, s46, v3
	v_or_b32_e32 v46, s48, v3
	v_lshl_add_u64 v[40:41], v[32:33], 0, v[40:41]
	v_lshl_add_u64 v[58:59], v[32:33], 0, v[58:59]
	global_load_dword v72, v[56:57], off
	global_load_dword v73, v[40:41], off
	global_load_dword v74, v[58:59], off
	global_load_dword v75, v[42:43], off
	v_lshlrev_b64 v[42:43], 14, v[4:5]
	v_or_b32_e32 v4, s56, v34
	s_add_i32 s55, s13, 16
	s_add_i32 s57, s13, 20
	s_add_i32 s60, s15, 24
	v_lshlrev_b64 v[44:45], 14, v[44:45]
	v_lshlrev_b64 v[46:47], 14, v[46:47]
	v_lshl_add_u64 v[40:41], v[32:33], 0, v[60:61]
	v_lshl_add_u64 v[42:43], v[32:33], 0, v[42:43]
	v_lshlrev_b64 v[56:57], 14, v[4:5]
	v_or_b32_e32 v4, s58, v34
	v_mov_b32_e32 v49, v5
	v_mov_b32_e32 v51, v5
	s_add_i32 s59, s13, 24
	s_add_i32 s61, s13, 28
	s_add_i32 s62, s15, 28
	v_or_b32_e32 v48, s55, v3
	v_or_b32_e32 v50, s57, v3
	v_lshl_add_u64 v[44:45], v[32:33], 0, v[44:45]
	v_lshl_add_u64 v[46:47], v[32:33], 0, v[46:47]
	global_load_dword v76, v[40:41], off
	global_load_dword v77, v[44:45], off
	global_load_dword v78, v[42:43], off
	global_load_dword v79, v[46:47], off
	v_lshlrev_b64 v[42:43], 14, v[4:5]
	v_or_b32_e32 v4, s60, v34
	v_mov_b32_e32 v53, v5
	v_mov_b32_e32 v55, v5
	v_or_b32_e32 v52, s59, v3
	v_or_b32_e32 v54, s61, v3
	v_lshlrev_b64 v[48:49], 14, v[48:49]
	v_lshlrev_b64 v[50:51], 14, v[50:51]
	v_lshl_add_u64 v[40:41], v[32:33], 0, v[56:57]
	v_lshl_add_u64 v[42:43], v[32:33], 0, v[42:43]
	v_lshlrev_b64 v[44:45], 14, v[4:5]
	v_or_b32_e32 v4, s62, v34
	v_lshlrev_b64 v[52:53], 14, v[52:53]
	v_lshlrev_b64 v[54:55], 14, v[54:55]
	v_lshl_add_u64 v[48:49], v[32:33], 0, v[48:49]
	v_lshl_add_u64 v[50:51], v[32:33], 0, v[50:51]
	global_load_dword v80, v[40:41], off
	global_load_dword v81, v[48:49], off
	global_load_dword v82, v[42:43], off
	global_load_dword v83, v[50:51], off
	v_lshl_add_u64 v[40:41], v[32:33], 0, v[44:45]
	v_lshlrev_b64 v[42:43], 14, v[4:5]
	v_lshl_add_u64 v[52:53], v[32:33], 0, v[52:53]
	v_lshl_add_u64 v[54:55], v[32:33], 0, v[54:55]
	v_lshl_add_u64 v[42:43], v[32:33], 0, v[42:43]
	global_load_dword v4, v[40:41], off
	global_load_dword v84, v[52:53], off
	global_load_dword v85, v[42:43], off
	global_load_dword v86, v[54:55], off
	v_or_b32_e32 v42, s13, v1
	v_or_b32_e32 v40, s15, v2
	s_add_i32 s0, s0, 16
	s_add_i32 s7, s7, 16
	s_add_i32 s12, s12, -16
	v_mad_u64_u32 v[40:41], s[20:21], v40, s5, v[8:9]
	v_mad_u64_u32 v[42:43], s[20:21], v42, s5, v[8:9]
	v_or_b32_e32 v41, s30, v1
	v_or_b32_e32 v43, s31, v2
	v_or_b32_e32 v50, s46, v1
	v_or_b32_e32 v48, s47, v2
	v_or_b32_e32 v54, s48, v1
	v_or_b32_e32 v52, s49, v2
	v_or_b32_e32 v58, s55, v1
	v_or_b32_e32 v56, s56, v2
	v_or_b32_e32 v62, s57, v1
	v_or_b32_e32 v60, s58, v2
	v_or_b32_e32 v66, s59, v1
	v_or_b32_e32 v64, s60, v2
	v_or_b32_e32 v70, s61, v1
	v_or_b32_e32 v68, s62, v2
	s_cmp_lg_u32 s12, 0
	v_mad_u64_u32 v[44:45], s[20:21], v43, s5, v[8:9]
	v_mad_u64_u32 v[46:47], s[20:21], v41, s5, v[8:9]
	v_mad_u64_u32 v[48:49], s[20:21], v48, s5, v[8:9]
	v_mad_u64_u32 v[50:51], s[20:21], v50, s5, v[8:9]
	v_mad_u64_u32 v[52:53], s[20:21], v52, s5, v[8:9]
	v_mad_u64_u32 v[54:55], s[20:21], v54, s5, v[8:9]
	v_mad_u64_u32 v[56:57], s[20:21], v56, s5, v[8:9]
	v_mad_u64_u32 v[58:59], s[20:21], v58, s5, v[8:9]
	v_mad_u64_u32 v[60:61], s[20:21], v60, s5, v[8:9]
	v_mad_u64_u32 v[62:63], s[20:21], v62, s5, v[8:9]
	v_mad_u64_u32 v[64:65], s[20:21], v64, s5, v[8:9]
	v_mad_u64_u32 v[66:67], s[20:21], v66, s5, v[8:9]
	v_mad_u64_u32 v[68:69], s[20:21], v68, s5, v[8:9]
	v_mad_u64_u32 v[70:71], s[20:21], v70, s5, v[8:9]
	s_waitcnt vmcnt(15)
	ds_write_b32 v40, v72
	s_waitcnt vmcnt(14)
	ds_write_b32 v42, v73
	s_waitcnt vmcnt(13)
	ds_write_b32 v44, v74
	s_waitcnt vmcnt(12)
	ds_write_b32 v46, v75
	s_waitcnt vmcnt(11)
	ds_write_b32 v48, v76
	s_waitcnt vmcnt(10)
	ds_write_b32 v50, v77
	s_waitcnt vmcnt(9)
	ds_write_b32 v52, v78
	s_waitcnt vmcnt(8)
	ds_write_b32 v54, v79
	s_waitcnt vmcnt(7)
	ds_write_b32 v56, v80
	s_waitcnt vmcnt(6)
	ds_write_b32 v58, v81
	s_waitcnt vmcnt(5)
	ds_write_b32 v60, v82
	s_waitcnt vmcnt(4)
	ds_write_b32 v62, v83
	s_waitcnt vmcnt(3)
	ds_write_b32 v64, v4
	s_waitcnt vmcnt(2)
	ds_write_b32 v66, v84
	s_waitcnt vmcnt(1)
	ds_write_b32 v68, v85
	s_waitcnt vmcnt(0)
	ds_write_b32 v70, v86
	s_cbranch_scc1 .LBB0_82
	s_waitcnt lgkmcnt(0)
	s_lshl_b32 s7, s19, 7
	s_lshl_b32 s12, s19, 4
	s_and_b32 s13, s14, 0xf00
	s_lshl_b32 s0, s6, 1
	s_and_b32 s6, s7, 0x80
	ds_read2_b32 v[72:73], v36 offset1:33
	ds_read2_b32 v[74:75], v36 offset0:66 offset1:99
	ds_read2_b32 v[76:77], v36 offset0:132 offset1:165
	ds_read2_b32 v[78:79], v36 offset0:198 offset1:231
	ds_read2_b32 v[80:81], v36 offset0:8 offset1:41
	ds_read2_b32 v[82:83], v36 offset0:74 offset1:107
	ds_read2_b32 v[84:85], v36 offset0:140 offset1:173
	ds_read2_b32 v[32:33], v36 offset0:206 offset1:239
	s_and_b32 s7, s12, 0x60
	v_lshl_add_u64 v[44:45], v[14:15], 0, s[0:1]
	s_or_b32 s0, s13, s6
	s_waitcnt lgkmcnt(7)
	v_cvt_pk_bf16_f32 v40, v72, v73
	s_or_b32 s0, s0, s7
	s_waitcnt lgkmcnt(6)
	v_cvt_pk_bf16_f32 v41, v74, v75
	v_or_b32_e32 v3, s0, v35
	s_waitcnt lgkmcnt(5)
	v_cvt_pk_bf16_f32 v42, v76, v77
	v_lshlrev_b32_e32 v4, 11, v3
	s_waitcnt lgkmcnt(4)
	v_cvt_pk_bf16_f32 v43, v78, v79
	v_lshl_add_u64 v[46:47], v[44:45], 0, v[4:5]
	global_store_dwordx4 v[46:47], v[40:43], off
	v_or_b32_e32 v3, s0, v37
	v_lshlrev_b32_e32 v4, 11, v3
	s_waitcnt lgkmcnt(3)
	v_cvt_pk_bf16_f32 v40, v80, v81
	s_waitcnt lgkmcnt(2)
	v_cvt_pk_bf16_f32 v41, v82, v83
	s_waitcnt lgkmcnt(1)
	v_cvt_pk_bf16_f32 v42, v84, v85
	s_waitcnt lgkmcnt(0)
	v_cvt_pk_bf16_f32 v43, v32, v33
	ds_read2_b32 v[72:73], v36 offset0:16 offset1:49
	ds_read2_b32 v[74:75], v36 offset0:82 offset1:115
	ds_read2_b32 v[76:77], v36 offset0:148 offset1:181
	ds_read2_b32 v[78:79], v36 offset0:214 offset1:247
	ds_read2_b32 v[80:81], v36 offset0:24 offset1:57
	ds_read2_b32 v[82:83], v36 offset0:90 offset1:123
	ds_read2_b32 v[84:85], v36 offset0:156 offset1:189
	ds_read2_b32 v[32:33], v36 offset0:222 offset1:255
	v_lshl_add_u64 v[46:47], v[44:45], 0, v[4:5]
	global_store_dwordx4 v[46:47], v[40:43], off
	v_or_b32_e32 v3, s0, v38
	v_lshlrev_b32_e32 v4, 11, v3
	s_waitcnt lgkmcnt(7)
	v_cvt_pk_bf16_f32 v40, v72, v73
	s_waitcnt lgkmcnt(6)
	v_cvt_pk_bf16_f32 v41, v74, v75
	s_waitcnt lgkmcnt(5)
	v_cvt_pk_bf16_f32 v42, v76, v77
	s_waitcnt lgkmcnt(4)
	v_cvt_pk_bf16_f32 v43, v78, v79
	v_lshl_add_u64 v[46:47], v[44:45], 0, v[4:5]
	global_store_dwordx4 v[46:47], v[40:43], off
	v_or_b32_e32 v3, s0, v39
	v_lshlrev_b32_e32 v4, 11, v3
	s_waitcnt lgkmcnt(3)
	v_cvt_pk_bf16_f32 v40, v80, v81
	s_waitcnt lgkmcnt(2)
	v_cvt_pk_bf16_f32 v41, v82, v83
	s_waitcnt lgkmcnt(1)
	v_cvt_pk_bf16_f32 v42, v84, v85
	s_waitcnt lgkmcnt(0)
	v_cvt_pk_bf16_f32 v43, v32, v33
	v_lshl_add_u64 v[32:33], v[44:45], 0, v[4:5]
	global_store_dwordx4 v[32:33], v[40:43], off
	s_waitcnt lgkmcnt(0)

.LBB0_87:
	s_lshl_b32 s15, s13, 1
	s_lshl_b32 s20, s0, 1
	v_or_b32_e32 v4, s20, v34
	s_add_i32 s30, s15, 4
	s_add_i32 s31, s20, 4
	v_mov_b32_e32 v43, v5
	s_add_i32 s47, s20, 8
	v_lshlrev_b64 v[56:57], 12, v[4:5]
	v_or_b32_e32 v42, s30, v3
	v_or_b32_e32 v4, s31, v34
	v_mov_b32_e32 v41, v5
	v_or_b32_e32 v40, s15, v3
	s_add_i32 s49, s20, 12
	v_lshlrev_b64 v[42:43], 12, v[42:43]
	v_lshlrev_b64 v[58:59], 12, v[4:5]
	v_or_b32_e32 v4, s47, v34
	s_add_i32 s46, s15, 8
	s_add_i32 s48, s15, 12
	s_add_i32 s56, s20, 16
	v_lshlrev_b64 v[40:41], 12, v[40:41]
	v_lshl_add_u64 v[56:57], v[32:33], 0, v[56:57]
	v_lshl_add_u64 v[42:43], v[32:33], 0, v[42:43]
	v_lshlrev_b64 v[60:61], 12, v[4:5]
	v_or_b32_e32 v4, s49, v34
	v_mov_b32_e32 v45, v5
	v_mov_b32_e32 v47, v5
	s_add_i32 s58, s20, 20
	v_or_b32_e32 v44, s46, v3
	v_or_b32_e32 v46, s48, v3
	v_lshl_add_u64 v[40:41], v[32:33], 0, v[40:41]
	v_lshl_add_u64 v[58:59], v[32:33], 0, v[58:59]
	global_load_dword v72, v[56:57], off
	global_load_dword v73, v[40:41], off
	global_load_dword v74, v[58:59], off
	global_load_dword v75, v[42:43], off
	v_lshlrev_b64 v[42:43], 12, v[4:5]
	v_or_b32_e32 v4, s56, v34
	s_add_i32 s55, s15, 16
	s_add_i32 s57, s15, 20
	s_add_i32 s60, s20, 24
	v_lshlrev_b64 v[44:45], 12, v[44:45]
	v_lshlrev_b64 v[46:47], 12, v[46:47]
	v_lshl_add_u64 v[40:41], v[32:33], 0, v[60:61]
	v_lshl_add_u64 v[42:43], v[32:33], 0, v[42:43]
	v_lshlrev_b64 v[56:57], 12, v[4:5]
	v_or_b32_e32 v4, s58, v34
	v_mov_b32_e32 v49, v5
	v_mov_b32_e32 v51, v5
	s_add_i32 s59, s15, 24
	s_add_i32 s61, s15, 28
	s_add_i32 s62, s20, 28
	v_or_b32_e32 v48, s55, v3
	v_or_b32_e32 v50, s57, v3
	v_lshl_add_u64 v[44:45], v[32:33], 0, v[44:45]
	v_lshl_add_u64 v[46:47], v[32:33], 0, v[46:47]
	global_load_dword v76, v[40:41], off
	global_load_dword v77, v[44:45], off
	global_load_dword v78, v[42:43], off
	global_load_dword v79, v[46:47], off
	v_lshlrev_b64 v[42:43], 12, v[4:5]
	v_or_b32_e32 v4, s60, v34
	v_mov_b32_e32 v53, v5
	v_mov_b32_e32 v55, v5
	v_or_b32_e32 v52, s59, v3
	v_or_b32_e32 v54, s61, v3
	v_lshlrev_b64 v[48:49], 12, v[48:49]
	v_lshlrev_b64 v[50:51], 12, v[50:51]
	v_lshl_add_u64 v[40:41], v[32:33], 0, v[56:57]
	v_lshl_add_u64 v[42:43], v[32:33], 0, v[42:43]
	v_lshlrev_b64 v[44:45], 12, v[4:5]
	v_or_b32_e32 v4, s62, v34
	v_lshlrev_b64 v[52:53], 12, v[52:53]
	v_lshlrev_b64 v[54:55], 12, v[54:55]
	v_lshl_add_u64 v[48:49], v[32:33], 0, v[48:49]
	v_lshl_add_u64 v[50:51], v[32:33], 0, v[50:51]
	global_load_dword v80, v[40:41], off
	global_load_dword v81, v[48:49], off
	global_load_dword v82, v[42:43], off
	global_load_dword v83, v[50:51], off
	v_lshl_add_u64 v[40:41], v[32:33], 0, v[44:45]
	v_lshlrev_b64 v[42:43], 12, v[4:5]
	v_lshl_add_u64 v[52:53], v[32:33], 0, v[52:53]
	v_lshl_add_u64 v[54:55], v[32:33], 0, v[54:55]
	v_lshl_add_u64 v[42:43], v[32:33], 0, v[42:43]
	global_load_dword v4, v[40:41], off
	global_load_dword v84, v[52:53], off
	global_load_dword v85, v[42:43], off
	global_load_dword v86, v[54:55], off
	v_or_b32_e32 v42, s15, v1
	v_or_b32_e32 v40, s20, v2
	s_add_i32 s0, s0, 16
	s_add_i32 s13, s13, 16
	s_add_i32 s14, s14, -16
	v_mad_u64_u32 v[40:41], s[20:21], v40, s5, v[8:9]
	v_mad_u64_u32 v[42:43], s[20:21], v42, s5, v[8:9]
	v_or_b32_e32 v41, s30, v1
	v_or_b32_e32 v43, s31, v2
	v_or_b32_e32 v50, s46, v1
	v_or_b32_e32 v48, s47, v2
	v_or_b32_e32 v54, s48, v1
	v_or_b32_e32 v52, s49, v2
	v_or_b32_e32 v58, s55, v1
	v_or_b32_e32 v56, s56, v2
	v_or_b32_e32 v62, s57, v1
	v_or_b32_e32 v60, s58, v2
	v_or_b32_e32 v66, s59, v1
	v_or_b32_e32 v64, s60, v2
	v_or_b32_e32 v70, s61, v1
	v_or_b32_e32 v68, s62, v2
	s_cmp_lg_u32 s14, 0
	v_mad_u64_u32 v[44:45], s[20:21], v43, s5, v[8:9]
	v_mad_u64_u32 v[46:47], s[20:21], v41, s5, v[8:9]
	v_mad_u64_u32 v[48:49], s[20:21], v48, s5, v[8:9]
	v_mad_u64_u32 v[50:51], s[20:21], v50, s5, v[8:9]
	v_mad_u64_u32 v[52:53], s[20:21], v52, s5, v[8:9]
	v_mad_u64_u32 v[54:55], s[20:21], v54, s5, v[8:9]
	v_mad_u64_u32 v[56:57], s[20:21], v56, s5, v[8:9]
	v_mad_u64_u32 v[58:59], s[20:21], v58, s5, v[8:9]
	v_mad_u64_u32 v[60:61], s[20:21], v60, s5, v[8:9]
	v_mad_u64_u32 v[62:63], s[20:21], v62, s5, v[8:9]
	v_mad_u64_u32 v[64:65], s[20:21], v64, s5, v[8:9]
	v_mad_u64_u32 v[66:67], s[20:21], v66, s5, v[8:9]
	v_mad_u64_u32 v[68:69], s[20:21], v68, s5, v[8:9]
	v_mad_u64_u32 v[70:71], s[20:21], v70, s5, v[8:9]
	s_waitcnt vmcnt(15)
	ds_write_b32 v40, v72
	s_waitcnt vmcnt(14)
	ds_write_b32 v42, v73
	s_waitcnt vmcnt(13)
	ds_write_b32 v44, v74
	s_waitcnt vmcnt(12)
	ds_write_b32 v46, v75
	s_waitcnt vmcnt(11)
	ds_write_b32 v48, v76
	s_waitcnt vmcnt(10)
	ds_write_b32 v50, v77
	s_waitcnt vmcnt(9)
	ds_write_b32 v52, v78
	s_waitcnt vmcnt(8)
	ds_write_b32 v54, v79
	s_waitcnt vmcnt(7)
	ds_write_b32 v56, v80
	s_waitcnt vmcnt(6)
	ds_write_b32 v58, v81
	s_waitcnt vmcnt(5)
	ds_write_b32 v60, v82
	s_waitcnt vmcnt(4)
	ds_write_b32 v62, v83
	s_waitcnt vmcnt(3)
	ds_write_b32 v64, v4
	s_waitcnt vmcnt(2)
	ds_write_b32 v66, v84
	s_waitcnt vmcnt(1)
	ds_write_b32 v68, v85
	s_waitcnt vmcnt(0)
	ds_write_b32 v70, v86
	s_cbranch_scc1 .LBB0_87
	s_waitcnt lgkmcnt(0)
	s_and_b32 s12, s12, 0x80
	s_lshl_b32 s13, s19, 4
	s_and_b32 s7, s7, 0x300
	ds_read2_b32 v[72:73], v36 offset1:33
	ds_read2_b32 v[74:75], v36 offset0:66 offset1:99
	ds_read2_b32 v[76:77], v36 offset0:132 offset1:165
	ds_read2_b32 v[78:79], v36 offset0:198 offset1:231
	ds_read2_b32 v[80:81], v36 offset0:8 offset1:41
	ds_read2_b32 v[82:83], v36 offset0:74 offset1:107
	ds_read2_b32 v[84:85], v36 offset0:140 offset1:173
	ds_read2_b32 v[32:33], v36 offset0:206 offset1:239
	s_lshl_b32 s0, s6, 1
	s_and_b32 s6, s13, 0x60
	s_or_b32 s7, s7, s12
	s_waitcnt lgkmcnt(7)
	v_cvt_pk_bf16_f32 v40, v72, v73
	v_lshl_add_u64 v[44:45], v[18:19], 0, s[0:1]
	s_or_b32 s0, s7, s6
	s_waitcnt lgkmcnt(6)
	v_cvt_pk_bf16_f32 v41, v74, v75
	v_or_b32_e32 v3, s0, v35
	s_waitcnt lgkmcnt(5)
	v_cvt_pk_bf16_f32 v42, v76, v77
	v_lshlrev_b32_e32 v4, 11, v3
	s_waitcnt lgkmcnt(4)
	v_cvt_pk_bf16_f32 v43, v78, v79
	v_lshl_add_u64 v[46:47], v[44:45], 0, v[4:5]
	global_store_dwordx4 v[46:47], v[40:43], off
	v_or_b32_e32 v3, s0, v37
	v_lshlrev_b32_e32 v4, 11, v3
	s_waitcnt lgkmcnt(3)
	v_cvt_pk_bf16_f32 v40, v80, v81
	s_waitcnt lgkmcnt(2)
	v_cvt_pk_bf16_f32 v41, v82, v83
	s_waitcnt lgkmcnt(1)
	v_cvt_pk_bf16_f32 v42, v84, v85
	s_waitcnt lgkmcnt(0)
	v_cvt_pk_bf16_f32 v43, v32, v33
	ds_read2_b32 v[72:73], v36 offset0:16 offset1:49
	ds_read2_b32 v[74:75], v36 offset0:82 offset1:115
	ds_read2_b32 v[76:77], v36 offset0:148 offset1:181
	ds_read2_b32 v[78:79], v36 offset0:214 offset1:247
	ds_read2_b32 v[80:81], v36 offset0:24 offset1:57
	ds_read2_b32 v[82:83], v36 offset0:90 offset1:123
	ds_read2_b32 v[84:85], v36 offset0:156 offset1:189
	ds_read2_b32 v[32:33], v36 offset0:222 offset1:255
	v_lshl_add_u64 v[46:47], v[44:45], 0, v[4:5]
	global_store_dwordx4 v[46:47], v[40:43], off
	v_or_b32_e32 v3, s0, v38
	v_lshlrev_b32_e32 v4, 11, v3
	s_waitcnt lgkmcnt(7)
	v_cvt_pk_bf16_f32 v40, v72, v73
	s_waitcnt lgkmcnt(6)
	v_cvt_pk_bf16_f32 v41, v74, v75
	s_waitcnt lgkmcnt(5)
	v_cvt_pk_bf16_f32 v42, v76, v77
	s_waitcnt lgkmcnt(4)
	v_cvt_pk_bf16_f32 v43, v78, v79
	v_lshl_add_u64 v[46:47], v[44:45], 0, v[4:5]
	global_store_dwordx4 v[46:47], v[40:43], off
	v_or_b32_e32 v3, s0, v39
	v_lshlrev_b32_e32 v4, 11, v3
	s_waitcnt lgkmcnt(3)
	v_cvt_pk_bf16_f32 v40, v80, v81
	s_waitcnt lgkmcnt(2)
	v_cvt_pk_bf16_f32 v41, v82, v83
	s_waitcnt lgkmcnt(1)
	v_cvt_pk_bf16_f32 v42, v84, v85
	s_waitcnt lgkmcnt(0)
	v_cvt_pk_bf16_f32 v43, v32, v33
	v_lshl_add_u64 v[32:33], v[44:45], 0, v[4:5]
	global_store_dwordx4 v[32:33], v[40:43], off
	s_waitcnt lgkmcnt(0)

.LBB0_92:
	s_lshl_b32 s14, s12, 1
	s_lshl_b32 s15, s0, 1
	v_or_b32_e32 v4, s15, v34
	s_add_i32 s20, s14, 4
	s_add_i32 s21, s15, 4
	v_mov_b32_e32 v43, v5
	s_add_i32 s31, s15, 8
	v_lshlrev_b64 v[56:57], 12, v[4:5]
	v_or_b32_e32 v42, s20, v3
	v_or_b32_e32 v4, s21, v34
	v_mov_b32_e32 v41, v5
	v_or_b32_e32 v40, s14, v3
	s_add_i32 s47, s15, 12
	v_lshlrev_b64 v[42:43], 12, v[42:43]
	v_lshlrev_b64 v[58:59], 12, v[4:5]
	v_or_b32_e32 v4, s31, v34
	s_add_i32 s30, s14, 8
	s_add_i32 s46, s14, 12
	s_add_i32 s49, s15, 16
	v_lshlrev_b64 v[40:41], 12, v[40:41]
	v_lshl_add_u64 v[56:57], v[32:33], 0, v[56:57]
	v_lshl_add_u64 v[42:43], v[32:33], 0, v[42:43]
	v_lshlrev_b64 v[60:61], 12, v[4:5]
	v_or_b32_e32 v4, s47, v34
	v_mov_b32_e32 v45, v5
	v_mov_b32_e32 v47, v5
	s_add_i32 s56, s15, 20
	v_or_b32_e32 v44, s30, v3
	v_or_b32_e32 v46, s46, v3
	v_lshl_add_u64 v[40:41], v[32:33], 0, v[40:41]
	v_lshl_add_u64 v[58:59], v[32:33], 0, v[58:59]
	global_load_dword v72, v[56:57], off
	global_load_dword v73, v[40:41], off
	global_load_dword v74, v[58:59], off
	global_load_dword v75, v[42:43], off
	v_lshlrev_b64 v[42:43], 12, v[4:5]
	v_or_b32_e32 v4, s49, v34
	s_add_i32 s48, s14, 16
	s_add_i32 s55, s14, 20
	s_add_i32 s58, s15, 24
	v_lshlrev_b64 v[44:45], 12, v[44:45]
	v_lshlrev_b64 v[46:47], 12, v[46:47]
	v_lshl_add_u64 v[40:41], v[32:33], 0, v[60:61]
	v_lshl_add_u64 v[42:43], v[32:33], 0, v[42:43]
	v_lshlrev_b64 v[56:57], 12, v[4:5]
	v_or_b32_e32 v4, s56, v34
	v_mov_b32_e32 v49, v5
	v_mov_b32_e32 v51, v5
	s_add_i32 s57, s14, 24
	s_add_i32 s59, s14, 28
	s_add_i32 s60, s15, 28
	v_or_b32_e32 v48, s48, v3
	v_or_b32_e32 v50, s55, v3
	v_lshl_add_u64 v[44:45], v[32:33], 0, v[44:45]
	v_lshl_add_u64 v[46:47], v[32:33], 0, v[46:47]
	global_load_dword v76, v[40:41], off
	global_load_dword v77, v[44:45], off
	global_load_dword v78, v[42:43], off
	global_load_dword v79, v[46:47], off
	v_lshlrev_b64 v[42:43], 12, v[4:5]
	v_or_b32_e32 v4, s58, v34
	v_mov_b32_e32 v53, v5
	v_mov_b32_e32 v55, v5
	v_or_b32_e32 v52, s57, v3
	v_or_b32_e32 v54, s59, v3
	v_lshlrev_b64 v[48:49], 12, v[48:49]
	v_lshlrev_b64 v[50:51], 12, v[50:51]
	v_lshl_add_u64 v[40:41], v[32:33], 0, v[56:57]
	v_lshl_add_u64 v[42:43], v[32:33], 0, v[42:43]
	v_lshlrev_b64 v[44:45], 12, v[4:5]
	v_or_b32_e32 v4, s60, v34
	v_lshlrev_b64 v[52:53], 12, v[52:53]
	v_lshlrev_b64 v[54:55], 12, v[54:55]
	v_lshl_add_u64 v[48:49], v[32:33], 0, v[48:49]
	v_lshl_add_u64 v[50:51], v[32:33], 0, v[50:51]
	global_load_dword v80, v[40:41], off
	global_load_dword v81, v[48:49], off
	global_load_dword v82, v[42:43], off
	global_load_dword v83, v[50:51], off
	v_lshl_add_u64 v[40:41], v[32:33], 0, v[44:45]
	v_lshlrev_b64 v[42:43], 12, v[4:5]
	v_lshl_add_u64 v[52:53], v[32:33], 0, v[52:53]
	v_lshl_add_u64 v[54:55], v[32:33], 0, v[54:55]
	v_lshl_add_u64 v[42:43], v[32:33], 0, v[42:43]
	global_load_dword v4, v[40:41], off
	global_load_dword v84, v[52:53], off
	global_load_dword v85, v[42:43], off
	global_load_dword v86, v[54:55], off
	v_or_b32_e32 v42, s14, v1
	v_or_b32_e32 v40, s15, v2
	s_add_i32 s0, s0, 16
	s_add_i32 s12, s12, 16
	s_add_i32 s13, s13, -16
	v_mad_u64_u32 v[40:41], s[14:15], v40, s5, v[8:9]
	v_mad_u64_u32 v[42:43], s[14:15], v42, s5, v[8:9]
	v_or_b32_e32 v41, s20, v1
	v_or_b32_e32 v43, s21, v2
	v_or_b32_e32 v50, s30, v1
	v_or_b32_e32 v48, s31, v2
	v_or_b32_e32 v54, s46, v1
	v_or_b32_e32 v52, s47, v2
	v_or_b32_e32 v58, s48, v1
	v_or_b32_e32 v56, s49, v2
	v_or_b32_e32 v62, s55, v1
	v_or_b32_e32 v60, s56, v2
	v_or_b32_e32 v66, s57, v1
	v_or_b32_e32 v64, s58, v2
	v_or_b32_e32 v70, s59, v1
	v_or_b32_e32 v68, s60, v2
	s_cmp_lg_u32 s13, 0
	v_mad_u64_u32 v[44:45], s[14:15], v43, s5, v[8:9]
	v_mad_u64_u32 v[46:47], s[14:15], v41, s5, v[8:9]
	v_mad_u64_u32 v[48:49], s[14:15], v48, s5, v[8:9]
	v_mad_u64_u32 v[50:51], s[14:15], v50, s5, v[8:9]
	v_mad_u64_u32 v[52:53], s[14:15], v52, s5, v[8:9]
	v_mad_u64_u32 v[54:55], s[14:15], v54, s5, v[8:9]
	v_mad_u64_u32 v[56:57], s[14:15], v56, s5, v[8:9]
	v_mad_u64_u32 v[58:59], s[14:15], v58, s5, v[8:9]
	v_mad_u64_u32 v[60:61], s[14:15], v60, s5, v[8:9]
	v_mad_u64_u32 v[62:63], s[14:15], v62, s5, v[8:9]
	v_mad_u64_u32 v[64:65], s[14:15], v64, s5, v[8:9]
	v_mad_u64_u32 v[66:67], s[14:15], v66, s5, v[8:9]
	v_mad_u64_u32 v[68:69], s[14:15], v68, s5, v[8:9]
	v_mad_u64_u32 v[70:71], s[14:15], v70, s5, v[8:9]
	s_waitcnt vmcnt(15)
	ds_write_b32 v40, v72
	s_waitcnt vmcnt(14)
	ds_write_b32 v42, v73
	s_waitcnt vmcnt(13)
	ds_write_b32 v44, v74
	s_waitcnt vmcnt(12)
	ds_write_b32 v46, v75
	s_waitcnt vmcnt(11)
	ds_write_b32 v48, v76
	s_waitcnt vmcnt(10)
	ds_write_b32 v50, v77
	s_waitcnt vmcnt(9)
	ds_write_b32 v52, v78
	s_waitcnt vmcnt(8)
	ds_write_b32 v54, v79
	s_waitcnt vmcnt(7)
	ds_write_b32 v56, v80
	s_waitcnt vmcnt(6)
	ds_write_b32 v58, v81
	s_waitcnt vmcnt(5)
	ds_write_b32 v60, v82
	s_waitcnt vmcnt(4)
	ds_write_b32 v62, v83
	s_waitcnt vmcnt(3)
	ds_write_b32 v64, v4
	s_waitcnt vmcnt(2)
	ds_write_b32 v66, v84
	s_waitcnt vmcnt(1)
	ds_write_b32 v68, v85
	s_waitcnt vmcnt(0)
	ds_write_b32 v70, v86
	s_cbranch_scc1 .LBB0_92
	s_waitcnt lgkmcnt(0)
	ds_read2_b32 v[72:73], v36 offset1:33
	ds_read2_b32 v[74:75], v36 offset0:66 offset1:99
	ds_read2_b32 v[76:77], v36 offset0:132 offset1:165
	ds_read2_b32 v[78:79], v36 offset0:198 offset1:231
	ds_read2_b32 v[80:81], v36 offset0:8 offset1:41
	ds_read2_b32 v[82:83], v36 offset0:74 offset1:107
	ds_read2_b32 v[84:85], v36 offset0:140 offset1:173
	ds_read2_b32 v[32:33], v36 offset0:206 offset1:239
	s_waitcnt lgkmcnt(7)
	v_cvt_pk_bf16_f32 v40, v72, v73
	s_waitcnt lgkmcnt(6)
	v_cvt_pk_bf16_f32 v41, v74, v75
	s_lshl_b32 s0, s7, 1
	v_or_b32_e32 v3, s6, v35
	s_waitcnt lgkmcnt(5)
	v_cvt_pk_bf16_f32 v42, v76, v77
	v_lshl_add_u64 v[44:45], v[22:23], 0, s[0:1]
	v_lshlrev_b32_e32 v4, 10, v3
	s_waitcnt lgkmcnt(4)
	v_cvt_pk_bf16_f32 v43, v78, v79
	v_lshl_add_u64 v[46:47], v[44:45], 0, v[4:5]
	global_store_dwordx4 v[46:47], v[40:43], off
	v_or_b32_e32 v3, s6, v37
	v_lshlrev_b32_e32 v4, 10, v3
	s_waitcnt lgkmcnt(3)
	v_cvt_pk_bf16_f32 v40, v80, v81
	s_waitcnt lgkmcnt(2)
	v_cvt_pk_bf16_f32 v41, v82, v83
	s_waitcnt lgkmcnt(1)
	v_cvt_pk_bf16_f32 v42, v84, v85
	s_waitcnt lgkmcnt(0)
	v_cvt_pk_bf16_f32 v43, v32, v33
	ds_read2_b32 v[72:73], v36 offset0:16 offset1:49
	ds_read2_b32 v[74:75], v36 offset0:82 offset1:115
	ds_read2_b32 v[76:77], v36 offset0:148 offset1:181
	ds_read2_b32 v[78:79], v36 offset0:214 offset1:247
	ds_read2_b32 v[80:81], v36 offset0:24 offset1:57
	ds_read2_b32 v[82:83], v36 offset0:90 offset1:123
	ds_read2_b32 v[84:85], v36 offset0:156 offset1:189
	ds_read2_b32 v[32:33], v36 offset0:222 offset1:255
	v_lshl_add_u64 v[46:47], v[44:45], 0, v[4:5]
	global_store_dwordx4 v[46:47], v[40:43], off
	v_or_b32_e32 v3, s6, v38
	v_lshlrev_b32_e32 v4, 10, v3
	s_waitcnt lgkmcnt(7)
	v_cvt_pk_bf16_f32 v40, v72, v73
	s_waitcnt lgkmcnt(6)
	v_cvt_pk_bf16_f32 v41, v74, v75
	s_waitcnt lgkmcnt(5)
	v_cvt_pk_bf16_f32 v42, v76, v77
	s_waitcnt lgkmcnt(4)
	v_cvt_pk_bf16_f32 v43, v78, v79
	v_lshl_add_u64 v[46:47], v[44:45], 0, v[4:5]
	global_store_dwordx4 v[46:47], v[40:43], off
	v_or_b32_e32 v3, s6, v39
	v_lshlrev_b32_e32 v4, 10, v3
	s_waitcnt lgkmcnt(3)
	v_cvt_pk_bf16_f32 v40, v80, v81
	s_waitcnt lgkmcnt(2)
	v_cvt_pk_bf16_f32 v41, v82, v83
	s_waitcnt lgkmcnt(1)
	v_cvt_pk_bf16_f32 v42, v84, v85
	s_waitcnt lgkmcnt(0)
	v_cvt_pk_bf16_f32 v43, v32, v33
	v_lshl_add_u64 v[32:33], v[44:45], 0, v[4:5]
	global_store_dwordx4 v[32:33], v[40:43], off
	s_waitcnt lgkmcnt(0)

.LBB0_97:
	s_lshl_b32 s14, s12, 1
	s_lshl_b32 s15, s0, 1
	v_or_b32_e32 v4, s15, v34
	s_add_i32 s20, s14, 4
	s_add_i32 s21, s15, 4
	v_mov_b32_e32 v43, v5
	s_add_i32 s31, s15, 8
	v_lshlrev_b64 v[56:57], 12, v[4:5]
	v_or_b32_e32 v42, s20, v3
	v_or_b32_e32 v4, s21, v34
	v_mov_b32_e32 v41, v5
	v_or_b32_e32 v40, s14, v3
	s_add_i32 s47, s15, 12
	v_lshlrev_b64 v[42:43], 12, v[42:43]
	v_lshlrev_b64 v[58:59], 12, v[4:5]
	v_or_b32_e32 v4, s31, v34
	s_add_i32 s30, s14, 8
	s_add_i32 s46, s14, 12
	s_add_i32 s49, s15, 16
	v_lshlrev_b64 v[40:41], 12, v[40:41]
	v_lshl_add_u64 v[56:57], v[32:33], 0, v[56:57]
	v_lshl_add_u64 v[42:43], v[32:33], 0, v[42:43]
	v_lshlrev_b64 v[60:61], 12, v[4:5]
	v_or_b32_e32 v4, s47, v34
	v_mov_b32_e32 v45, v5
	v_mov_b32_e32 v47, v5
	s_add_i32 s56, s15, 20
	v_or_b32_e32 v44, s30, v3
	v_or_b32_e32 v46, s46, v3
	v_lshl_add_u64 v[40:41], v[32:33], 0, v[40:41]
	v_lshl_add_u64 v[58:59], v[32:33], 0, v[58:59]
	global_load_dword v72, v[56:57], off
	global_load_dword v73, v[40:41], off
	global_load_dword v74, v[58:59], off
	global_load_dword v75, v[42:43], off
	v_lshlrev_b64 v[42:43], 12, v[4:5]
	v_or_b32_e32 v4, s49, v34
	s_add_i32 s48, s14, 16
	s_add_i32 s55, s14, 20
	s_add_i32 s58, s15, 24
	v_lshlrev_b64 v[44:45], 12, v[44:45]
	v_lshlrev_b64 v[46:47], 12, v[46:47]
	v_lshl_add_u64 v[40:41], v[32:33], 0, v[60:61]
	v_lshl_add_u64 v[42:43], v[32:33], 0, v[42:43]
	v_lshlrev_b64 v[56:57], 12, v[4:5]
	v_or_b32_e32 v4, s56, v34
	v_mov_b32_e32 v49, v5
	v_mov_b32_e32 v51, v5
	s_add_i32 s57, s14, 24
	s_add_i32 s59, s14, 28
	s_add_i32 s60, s15, 28
	v_or_b32_e32 v48, s48, v3
	v_or_b32_e32 v50, s55, v3
	v_lshl_add_u64 v[44:45], v[32:33], 0, v[44:45]
	v_lshl_add_u64 v[46:47], v[32:33], 0, v[46:47]
	global_load_dword v76, v[40:41], off
	global_load_dword v77, v[44:45], off
	global_load_dword v78, v[42:43], off
	global_load_dword v79, v[46:47], off
	v_lshlrev_b64 v[42:43], 12, v[4:5]
	v_or_b32_e32 v4, s58, v34
	v_mov_b32_e32 v53, v5
	v_mov_b32_e32 v55, v5
	v_or_b32_e32 v52, s57, v3
	v_or_b32_e32 v54, s59, v3
	v_lshlrev_b64 v[48:49], 12, v[48:49]
	v_lshlrev_b64 v[50:51], 12, v[50:51]
	v_lshl_add_u64 v[40:41], v[32:33], 0, v[56:57]
	v_lshl_add_u64 v[42:43], v[32:33], 0, v[42:43]
	v_lshlrev_b64 v[44:45], 12, v[4:5]
	v_or_b32_e32 v4, s60, v34
	v_lshlrev_b64 v[52:53], 12, v[52:53]
	v_lshlrev_b64 v[54:55], 12, v[54:55]
	v_lshl_add_u64 v[48:49], v[32:33], 0, v[48:49]
	v_lshl_add_u64 v[50:51], v[32:33], 0, v[50:51]
	global_load_dword v80, v[40:41], off
	global_load_dword v81, v[48:49], off
	global_load_dword v82, v[42:43], off
	global_load_dword v83, v[50:51], off
	v_lshl_add_u64 v[40:41], v[32:33], 0, v[44:45]
	v_lshlrev_b64 v[42:43], 12, v[4:5]
	v_lshl_add_u64 v[52:53], v[32:33], 0, v[52:53]
	v_lshl_add_u64 v[54:55], v[32:33], 0, v[54:55]
	v_lshl_add_u64 v[42:43], v[32:33], 0, v[42:43]
	global_load_dword v4, v[40:41], off
	global_load_dword v84, v[52:53], off
	global_load_dword v85, v[42:43], off
	global_load_dword v86, v[54:55], off
	v_or_b32_e32 v42, s14, v1
	v_or_b32_e32 v40, s15, v2
	s_add_i32 s0, s0, 16
	s_add_i32 s12, s12, 16
	s_add_i32 s13, s13, -16
	v_mad_u64_u32 v[40:41], s[14:15], v40, s5, v[8:9]
	v_mad_u64_u32 v[42:43], s[14:15], v42, s5, v[8:9]
	v_or_b32_e32 v41, s20, v1
	v_or_b32_e32 v43, s21, v2
	v_or_b32_e32 v50, s30, v1
	v_or_b32_e32 v48, s31, v2
	v_or_b32_e32 v54, s46, v1
	v_or_b32_e32 v52, s47, v2
	v_or_b32_e32 v58, s48, v1
	v_or_b32_e32 v56, s49, v2
	v_or_b32_e32 v62, s55, v1
	v_or_b32_e32 v60, s56, v2
	v_or_b32_e32 v66, s57, v1
	v_or_b32_e32 v64, s58, v2
	v_or_b32_e32 v70, s59, v1
	v_or_b32_e32 v68, s60, v2
	s_cmp_lg_u32 s13, 0
	v_mad_u64_u32 v[44:45], s[14:15], v43, s5, v[8:9]
	v_mad_u64_u32 v[46:47], s[14:15], v41, s5, v[8:9]
	v_mad_u64_u32 v[48:49], s[14:15], v48, s5, v[8:9]
	v_mad_u64_u32 v[50:51], s[14:15], v50, s5, v[8:9]
	v_mad_u64_u32 v[52:53], s[14:15], v52, s5, v[8:9]
	v_mad_u64_u32 v[54:55], s[14:15], v54, s5, v[8:9]
	v_mad_u64_u32 v[56:57], s[14:15], v56, s5, v[8:9]
	v_mad_u64_u32 v[58:59], s[14:15], v58, s5, v[8:9]
	v_mad_u64_u32 v[60:61], s[14:15], v60, s5, v[8:9]
	v_mad_u64_u32 v[62:63], s[14:15], v62, s5, v[8:9]
	v_mad_u64_u32 v[64:65], s[14:15], v64, s5, v[8:9]
	v_mad_u64_u32 v[66:67], s[14:15], v66, s5, v[8:9]
	v_mad_u64_u32 v[68:69], s[14:15], v68, s5, v[8:9]
	v_mad_u64_u32 v[70:71], s[14:15], v70, s5, v[8:9]
	s_waitcnt vmcnt(15)
	ds_write_b32 v40, v72
	s_waitcnt vmcnt(14)
	ds_write_b32 v42, v73
	s_waitcnt vmcnt(13)
	ds_write_b32 v44, v74
	s_waitcnt vmcnt(12)
	ds_write_b32 v46, v75
	s_waitcnt vmcnt(11)
	ds_write_b32 v48, v76
	s_waitcnt vmcnt(10)
	ds_write_b32 v50, v77
	s_waitcnt vmcnt(9)
	ds_write_b32 v52, v78
	s_waitcnt vmcnt(8)
	ds_write_b32 v54, v79
	s_waitcnt vmcnt(7)
	ds_write_b32 v56, v80
	s_waitcnt vmcnt(6)
	ds_write_b32 v58, v81
	s_waitcnt vmcnt(5)
	ds_write_b32 v60, v82
	s_waitcnt vmcnt(4)
	ds_write_b32 v62, v83
	s_waitcnt vmcnt(3)
	ds_write_b32 v64, v4
	s_waitcnt vmcnt(2)
	ds_write_b32 v66, v84
	s_waitcnt vmcnt(1)
	ds_write_b32 v68, v85
	s_waitcnt vmcnt(0)
	ds_write_b32 v70, v86
	s_cbranch_scc1 .LBB0_97
	s_waitcnt lgkmcnt(0)
	ds_read2_b32 v[72:73], v36 offset1:33
	ds_read2_b32 v[74:75], v36 offset0:66 offset1:99
	ds_read2_b32 v[76:77], v36 offset0:132 offset1:165
	ds_read2_b32 v[78:79], v36 offset0:198 offset1:231
	ds_read2_b32 v[80:81], v36 offset0:8 offset1:41
	ds_read2_b32 v[82:83], v36 offset0:74 offset1:107
	ds_read2_b32 v[84:85], v36 offset0:140 offset1:173
	ds_read2_b32 v[32:33], v36 offset0:206 offset1:239
	s_waitcnt lgkmcnt(7)
	v_cvt_pk_bf16_f32 v40, v72, v73
	s_waitcnt lgkmcnt(6)
	v_cvt_pk_bf16_f32 v41, v74, v75
	s_lshl_b32 s0, s7, 1
	v_or_b32_e32 v3, s6, v35
	s_waitcnt lgkmcnt(5)
	v_cvt_pk_bf16_f32 v42, v76, v77
	v_lshl_add_u64 v[44:45], v[26:27], 0, s[0:1]
	v_lshlrev_b32_e32 v4, 10, v3
	s_waitcnt lgkmcnt(4)
	v_cvt_pk_bf16_f32 v43, v78, v79
	v_lshl_add_u64 v[46:47], v[44:45], 0, v[4:5]
	global_store_dwordx4 v[46:47], v[40:43], off
	v_or_b32_e32 v3, s6, v37
	v_lshlrev_b32_e32 v4, 10, v3
	s_waitcnt lgkmcnt(3)
	v_cvt_pk_bf16_f32 v40, v80, v81
	s_waitcnt lgkmcnt(2)
	v_cvt_pk_bf16_f32 v41, v82, v83
	s_waitcnt lgkmcnt(1)
	v_cvt_pk_bf16_f32 v42, v84, v85
	s_waitcnt lgkmcnt(0)
	v_cvt_pk_bf16_f32 v43, v32, v33
	ds_read2_b32 v[72:73], v36 offset0:16 offset1:49
	ds_read2_b32 v[74:75], v36 offset0:82 offset1:115
	ds_read2_b32 v[76:77], v36 offset0:148 offset1:181
	ds_read2_b32 v[78:79], v36 offset0:214 offset1:247
	ds_read2_b32 v[80:81], v36 offset0:24 offset1:57
	ds_read2_b32 v[82:83], v36 offset0:90 offset1:123
	ds_read2_b32 v[84:85], v36 offset0:156 offset1:189
	ds_read2_b32 v[32:33], v36 offset0:222 offset1:255
	v_lshl_add_u64 v[46:47], v[44:45], 0, v[4:5]
	global_store_dwordx4 v[46:47], v[40:43], off
	v_or_b32_e32 v3, s6, v38
	v_lshlrev_b32_e32 v4, 10, v3
	s_waitcnt lgkmcnt(7)
	v_cvt_pk_bf16_f32 v40, v72, v73
	s_waitcnt lgkmcnt(6)
	v_cvt_pk_bf16_f32 v41, v74, v75
	s_waitcnt lgkmcnt(5)
	v_cvt_pk_bf16_f32 v42, v76, v77
	s_waitcnt lgkmcnt(4)
	v_cvt_pk_bf16_f32 v43, v78, v79
	v_lshl_add_u64 v[46:47], v[44:45], 0, v[4:5]
	global_store_dwordx4 v[46:47], v[40:43], off
	v_or_b32_e32 v3, s6, v39
	v_lshlrev_b32_e32 v4, 10, v3
	s_waitcnt lgkmcnt(3)
	v_cvt_pk_bf16_f32 v40, v80, v81
	s_waitcnt lgkmcnt(2)
	v_cvt_pk_bf16_f32 v41, v82, v83
	s_waitcnt lgkmcnt(1)
	v_cvt_pk_bf16_f32 v42, v84, v85
	s_waitcnt lgkmcnt(0)
	v_cvt_pk_bf16_f32 v43, v32, v33
	v_lshl_add_u64 v[32:33], v[44:45], 0, v[4:5]
	global_store_dwordx4 v[32:33], v[40:43], off
	s_waitcnt lgkmcnt(0)

.LBB0_102:
	s_lshl_b32 s15, s6, 1
	s_lshl_b32 s30, s7, 1
	v_or_b32_e32 v34, s15, v3
	v_or_b32_e32 v40, s30, v4
	s_add_i32 s31, s15, 4
	s_add_i32 s46, s30, 4
	s_add_i32 s47, s15, 8
	s_add_i32 s48, s30, 8
	s_add_i32 s49, s15, 12
	s_add_i32 s55, s30, 12
	s_add_i32 s56, s15, 16
	s_add_i32 s57, s30, 16
	s_add_i32 s58, s15, 20
	s_add_i32 s59, s30, 20
	s_add_i32 s60, s15, 24
	s_add_i32 s61, s30, 24
	s_add_i32 s62, s15, 28
	s_add_i32 s63, s30, 28
	v_mad_i64_i32 v[40:41], s[20:21], v40, s18, v[32:33]
	v_mad_i64_i32 v[42:43], s[20:21], v34, s18, v[32:33]
	v_or_b32_e32 v34, s31, v3
	v_or_b32_e32 v44, s46, v4
	v_or_b32_e32 v50, s47, v3
	v_or_b32_e32 v48, s48, v4
	v_or_b32_e32 v54, s49, v3
	v_or_b32_e32 v52, s55, v4
	v_or_b32_e32 v58, s56, v3
	v_or_b32_e32 v56, s57, v4
	v_or_b32_e32 v62, s58, v3
	v_or_b32_e32 v60, s59, v4
	v_or_b32_e32 v66, s60, v3
	v_or_b32_e32 v64, s61, v4
	v_or_b32_e32 v70, s62, v3
	v_or_b32_e32 v68, s63, v4
	v_mad_i64_i32 v[44:45], s[20:21], v44, s18, v[32:33]
	v_mad_i64_i32 v[46:47], s[20:21], v34, s18, v[32:33]
	v_mad_i64_i32 v[48:49], s[20:21], v48, s18, v[32:33]
	v_mad_i64_i32 v[50:51], s[20:21], v50, s18, v[32:33]
	v_mad_i64_i32 v[52:53], s[20:21], v52, s18, v[32:33]
	v_mad_i64_i32 v[54:55], s[20:21], v54, s18, v[32:33]
	v_mad_i64_i32 v[56:57], s[20:21], v56, s18, v[32:33]
	v_mad_i64_i32 v[58:59], s[20:21], v58, s18, v[32:33]
	v_mad_i64_i32 v[60:61], s[20:21], v60, s18, v[32:33]
	v_mad_i64_i32 v[62:63], s[20:21], v62, s18, v[32:33]
	v_mad_i64_i32 v[64:65], s[20:21], v64, s18, v[32:33]
	v_mad_i64_i32 v[66:67], s[20:21], v66, s18, v[32:33]
	v_mad_i64_i32 v[68:69], s[20:21], v68, s18, v[32:33]
	v_mad_i64_i32 v[70:71], s[20:21], v70, s18, v[32:33]
	global_load_dword v34, v[40:41], off
	global_load_dword v72, v[42:43], off
	global_load_dword v73, v[44:45], off
	global_load_dword v74, v[46:47], off
	global_load_dword v75, v[48:49], off
	global_load_dword v76, v[50:51], off
	global_load_dword v77, v[52:53], off
	global_load_dword v78, v[54:55], off
	global_load_dword v79, v[56:57], off
	global_load_dword v80, v[58:59], off
	global_load_dword v81, v[60:61], off
	global_load_dword v82, v[62:63], off
	global_load_dword v83, v[64:65], off
	global_load_dword v84, v[66:67], off
	global_load_dword v85, v[68:69], off
	global_load_dword v86, v[70:71], off
	v_or_b32_e32 v42, s15, v1
	v_or_b32_e32 v40, s30, v2
	s_add_i32 s7, s7, 16
	s_add_i32 s6, s6, 16
	s_add_i32 s13, s13, -16
	v_mad_u64_u32 v[40:41], s[20:21], v40, s5, v[8:9]
	v_mad_u64_u32 v[42:43], s[20:21], v42, s5, v[8:9]
	v_or_b32_e32 v41, s31, v1
	v_or_b32_e32 v43, s46, v2
	v_or_b32_e32 v50, s47, v1
	v_or_b32_e32 v48, s48, v2
	v_or_b32_e32 v54, s49, v1
	v_or_b32_e32 v52, s55, v2
	v_or_b32_e32 v58, s56, v1
	v_or_b32_e32 v56, s57, v2
	v_or_b32_e32 v62, s58, v1
	v_or_b32_e32 v60, s59, v2
	v_or_b32_e32 v66, s60, v1
	v_or_b32_e32 v64, s61, v2
	v_or_b32_e32 v70, s62, v1
	v_or_b32_e32 v68, s63, v2
	s_cmp_lg_u32 s13, 0
	v_mad_u64_u32 v[44:45], s[20:21], v43, s5, v[8:9]
	v_mad_u64_u32 v[46:47], s[20:21], v41, s5, v[8:9]
	v_mad_u64_u32 v[48:49], s[20:21], v48, s5, v[8:9]
	v_mad_u64_u32 v[50:51], s[20:21], v50, s5, v[8:9]
	v_mad_u64_u32 v[52:53], s[20:21], v52, s5, v[8:9]
	v_mad_u64_u32 v[54:55], s[20:21], v54, s5, v[8:9]
	v_mad_u64_u32 v[56:57], s[20:21], v56, s5, v[8:9]
	v_mad_u64_u32 v[58:59], s[20:21], v58, s5, v[8:9]
	v_mad_u64_u32 v[60:61], s[20:21], v60, s5, v[8:9]
	v_mad_u64_u32 v[62:63], s[20:21], v62, s5, v[8:9]
	v_mad_u64_u32 v[64:65], s[20:21], v64, s5, v[8:9]
	v_mad_u64_u32 v[66:67], s[20:21], v66, s5, v[8:9]
	v_mad_u64_u32 v[68:69], s[20:21], v68, s5, v[8:9]
	v_mad_u64_u32 v[70:71], s[20:21], v70, s5, v[8:9]
	s_waitcnt vmcnt(15)
	ds_write_b32 v40, v34
	s_waitcnt vmcnt(14)
	ds_write_b32 v42, v72
	s_waitcnt vmcnt(13)
	ds_write_b32 v44, v73
	s_waitcnt vmcnt(12)
	ds_write_b32 v46, v74
	s_waitcnt vmcnt(11)
	ds_write_b32 v48, v75
	s_waitcnt vmcnt(10)
	ds_write_b32 v50, v76
	s_waitcnt vmcnt(9)
	ds_write_b32 v52, v77
	s_waitcnt vmcnt(8)
	ds_write_b32 v54, v78
	s_waitcnt vmcnt(7)
	ds_write_b32 v56, v79
	s_waitcnt vmcnt(6)
	ds_write_b32 v58, v80
	s_waitcnt vmcnt(5)
	ds_write_b32 v60, v81
	s_waitcnt vmcnt(4)
	ds_write_b32 v62, v82
	s_waitcnt vmcnt(3)
	ds_write_b32 v64, v83
	s_waitcnt vmcnt(2)
	ds_write_b32 v66, v84
	s_waitcnt vmcnt(1)
	ds_write_b32 v68, v85
	s_waitcnt vmcnt(0)
	ds_write_b32 v70, v86
	s_cbranch_scc1 .LBB0_102
	s_lshl_b32 s0, s0, 7
	s_waitcnt lgkmcnt(0)
	s_lshr_b32 s6, s14, 1
	s_and_b32 s7, s14, 0xffffff00
	s_and_b32 s0, s0, 0x80
	s_and_b32 s6, s6, 0x60
	s_or_b32 s0, s7, s0
	ds_read2_b32 v[72:73], v36 offset1:33
	ds_read2_b32 v[74:75], v36 offset0:66 offset1:99
	ds_read2_b32 v[76:77], v36 offset0:132 offset1:165
	ds_read2_b32 v[78:79], v36 offset0:198 offset1:231
	ds_read2_b32 v[80:81], v36 offset0:8 offset1:41
	ds_read2_b32 v[82:83], v36 offset0:74 offset1:107
	ds_read2_b32 v[84:85], v36 offset0:140 offset1:173
	ds_read2_b32 v[32:33], v36 offset0:206 offset1:239
	s_or_b32 s0, s0, s6
	s_waitcnt lgkmcnt(7)
	v_cvt_pk_bf16_f32 v40, v72, v73
	v_or_b32_e32 v46, s0, v35
	s_waitcnt lgkmcnt(6)
	v_cvt_pk_bf16_f32 v41, v74, v75
	s_ashr_i32 s13, s12, 31
	v_ashrrev_i32_e32 v47, 31, v46
	s_waitcnt lgkmcnt(5)
	v_cvt_pk_bf16_f32 v42, v76, v77
	v_lshl_add_u64 v[44:45], s[12:13], 1, v[30:31]
	v_lshlrev_b64 v[46:47], 11, v[46:47]
	s_waitcnt lgkmcnt(4)
	v_cvt_pk_bf16_f32 v43, v78, v79
	v_lshl_add_u64 v[46:47], v[44:45], 0, v[46:47]
	global_store_dwordx4 v[46:47], v[40:43], off
	v_or_b32_e32 v46, s0, v37
	v_ashrrev_i32_e32 v47, 31, v46
	s_waitcnt lgkmcnt(3)
	v_cvt_pk_bf16_f32 v40, v80, v81
	s_waitcnt lgkmcnt(2)
	v_cvt_pk_bf16_f32 v41, v82, v83
	s_waitcnt lgkmcnt(1)
	v_cvt_pk_bf16_f32 v42, v84, v85
	v_lshlrev_b64 v[46:47], 11, v[46:47]
	s_waitcnt lgkmcnt(0)
	v_cvt_pk_bf16_f32 v43, v32, v33
	ds_read2_b32 v[72:73], v36 offset0:16 offset1:49
	ds_read2_b32 v[74:75], v36 offset0:82 offset1:115
	ds_read2_b32 v[76:77], v36 offset0:148 offset1:181
	ds_read2_b32 v[78:79], v36 offset0:214 offset1:247
	ds_read2_b32 v[80:81], v36 offset0:24 offset1:57
	ds_read2_b32 v[82:83], v36 offset0:90 offset1:123
	ds_read2_b32 v[84:85], v36 offset0:156 offset1:189
	ds_read2_b32 v[32:33], v36 offset0:222 offset1:255
	v_lshl_add_u64 v[46:47], v[44:45], 0, v[46:47]
	global_store_dwordx4 v[46:47], v[40:43], off
	v_or_b32_e32 v46, s0, v38
	v_ashrrev_i32_e32 v47, 31, v46
	s_waitcnt lgkmcnt(7)
	v_cvt_pk_bf16_f32 v40, v72, v73
	s_waitcnt lgkmcnt(6)
	v_cvt_pk_bf16_f32 v41, v74, v75
	s_waitcnt lgkmcnt(5)
	v_cvt_pk_bf16_f32 v42, v76, v77
	v_lshlrev_b64 v[46:47], 11, v[46:47]
	s_waitcnt lgkmcnt(4)
	v_cvt_pk_bf16_f32 v43, v78, v79
	v_lshl_add_u64 v[46:47], v[44:45], 0, v[46:47]
	global_store_dwordx4 v[46:47], v[40:43], off
	v_or_b32_e32 v46, s0, v39
	v_ashrrev_i32_e32 v47, 31, v46
	s_waitcnt lgkmcnt(3)
	v_cvt_pk_bf16_f32 v40, v80, v81
	s_waitcnt lgkmcnt(2)
	v_cvt_pk_bf16_f32 v41, v82, v83
	s_waitcnt lgkmcnt(1)
	v_cvt_pk_bf16_f32 v42, v84, v85
	v_lshlrev_b64 v[46:47], 11, v[46:47]
	s_waitcnt lgkmcnt(0)
	v_cvt_pk_bf16_f32 v43, v32, v33
	v_lshl_add_u64 v[32:33], v[44:45], 0, v[46:47]
	global_store_dwordx4 v[32:33], v[40:43], off
	s_waitcnt lgkmcnt(0)
	s_branch .LBB0_71
